# P6 epilogue: the final_gain multiplies for three of every four stores (48 pk_mul, counted vmcnt(1)) hoisted from part 3 into the panel-exchange window
# baseline (speedup 1.0000x reference)
.LBB0_563:
	s_waitcnt vmcnt(1)
	v_pk_mul_f32 v[140:141], v[140:141], v[212:213]
	v_pk_mul_f32 v[142:143], v[142:143], v[214:215]
	v_pk_mul_f32 v[136:137], v[136:137], v[216:217]
	v_pk_mul_f32 v[138:139], v[138:139], v[218:219]
	v_pk_mul_f32 v[132:133], v[132:133], v[220:221]
	v_pk_mul_f32 v[134:135], v[134:135], v[222:223]
	v_pk_mul_f32 v[124:125], v[124:125], v[212:213]
	v_pk_mul_f32 v[126:127], v[126:127], v[214:215]
	v_pk_mul_f32 v[120:121], v[120:121], v[216:217]
	v_pk_mul_f32 v[122:123], v[122:123], v[218:219]
	v_pk_mul_f32 v[116:117], v[116:117], v[220:221]
	v_pk_mul_f32 v[118:119], v[118:119], v[222:223]
	v_pk_mul_f32 v[92:93], v[92:93], v[212:213]
	v_pk_mul_f32 v[94:95], v[94:95], v[214:215]
	v_pk_mul_f32 v[88:89], v[88:89], v[216:217]
	v_pk_mul_f32 v[90:91], v[90:91], v[218:219]
	v_pk_mul_f32 v[84:85], v[84:85], v[220:221]
	v_pk_mul_f32 v[86:87], v[86:87], v[222:223]
	v_pk_mul_f32 v[76:77], v[76:77], v[212:213]
	v_pk_mul_f32 v[78:79], v[78:79], v[214:215]
	v_pk_mul_f32 v[72:73], v[72:73], v[216:217]
	v_pk_mul_f32 v[74:75], v[74:75], v[218:219]
	v_pk_mul_f32 v[68:69], v[68:69], v[220:221]
	v_pk_mul_f32 v[70:71], v[70:71], v[222:223]
	v_pk_mul_f32 v[60:61], v[60:61], v[212:213]
	v_pk_mul_f32 v[62:63], v[62:63], v[214:215]
	v_pk_mul_f32 v[56:57], v[56:57], v[216:217]
	v_pk_mul_f32 v[58:59], v[58:59], v[218:219]
	v_pk_mul_f32 v[52:53], v[52:53], v[220:221]
	v_pk_mul_f32 v[54:55], v[54:55], v[222:223]
	v_pk_mul_f32 v[44:45], v[44:45], v[212:213]
	v_pk_mul_f32 v[46:47], v[46:47], v[214:215]
	v_pk_mul_f32 v[40:41], v[40:41], v[216:217]
	v_pk_mul_f32 v[42:43], v[42:43], v[218:219]
	v_pk_mul_f32 v[36:37], v[36:37], v[220:221]
	v_pk_mul_f32 v[38:39], v[38:39], v[222:223]
	v_pk_mul_f32 v[28:29], v[28:29], v[212:213]
	v_pk_mul_f32 v[30:31], v[30:31], v[214:215]
	v_pk_mul_f32 v[24:25], v[24:25], v[216:217]
	v_pk_mul_f32 v[26:27], v[26:27], v[218:219]
	v_pk_mul_f32 v[20:21], v[20:21], v[220:221]
	v_pk_mul_f32 v[22:23], v[22:23], v[222:223]
	v_pk_mul_f32 v[12:13], v[12:13], v[212:213]
	v_pk_mul_f32 v[14:15], v[14:15], v[214:215]
	v_pk_mul_f32 v[8:9], v[8:9], v[216:217]
	v_pk_mul_f32 v[10:11], v[10:11], v[218:219]
	v_pk_mul_f32 v[4:5], v[4:5], v[220:221]
	v_pk_mul_f32 v[6:7], v[6:7], v[222:223]
	s_waitcnt lgkmcnt(0)
	s_barrier
	s_and_b64 vcc, exec, s[2:3]
	s_cbranch_vccnz .LBB0_565
	v_lshlrev_b64 v[96:97], 5, v[96:97]
	v_lshl_add_u64 v[96:97], s[12:13], 0, v[96:97]
	s_mov_b32 s100, 0x400000
	s_sleep 16

.LBB0_565:
	s_waitcnt vmcnt(0) lgkmcnt(0)
	s_barrier
	v_lshl_add_u32 v245, v194, 2, 0
	v_add_u32_e32 v245, 0x21000, v245
	ds_read2_b32 v[228:229], v245 offset1:16
	ds_read2_b32 v[230:231], v245 offset0:32 offset1:48
	ds_read2_b32 v[232:233], v245 offset0:128 offset1:144
	ds_read2_b32 v[234:235], v245 offset0:160 offset1:176
	s_waitcnt lgkmcnt(0)
	v_mov_b32_e32 v242, v195
	v_lshl_add_u32 v242, v242, 13, v156
	v_pk_mul_f32 v[140:141], v[140:141], v[228:229] op_sel_hi:[1,0]
	v_pk_mul_f32 v[142:143], v[142:143], v[228:229] op_sel_hi:[1,0]
	global_store_dwordx4 v242, v[140:143], s[60:61]
	v_pk_mul_f32 v[136:137], v[136:137], v[228:229] op_sel_hi:[1,0]
	v_pk_mul_f32 v[138:139], v[138:139], v[228:229] op_sel_hi:[1,0]
	global_store_dwordx4 v242, v[136:139], s[60:61] offset:64
	v_pk_mul_f32 v[132:133], v[132:133], v[228:229] op_sel_hi:[1,0]
	v_pk_mul_f32 v[134:135], v[134:135], v[228:229] op_sel_hi:[1,0]
	global_store_dwordx4 v242, v[132:135], s[60:61] offset:512
	v_pk_mul_f32 v[128:129], v[128:129], v[228:229] op_sel_hi:[1,0]
	v_pk_mul_f32 v[130:131], v[130:131], v[228:229] op_sel_hi:[1,0]
	v_pk_mul_f32 v[128:129], v[128:129], v[224:225]
	v_pk_mul_f32 v[130:131], v[130:131], v[226:227]
	global_store_dwordx4 v242, v[128:131], s[60:61] offset:576
	v_add_u32_e32 v242, 16, v195
	v_lshl_add_u32 v242, v242, 13, v156
	v_pk_mul_f32 v[124:125], v[124:125], v[228:229] op_sel:[0,1] op_sel_hi:[1,1]
	v_pk_mul_f32 v[126:127], v[126:127], v[228:229] op_sel:[0,1] op_sel_hi:[1,1]
	global_store_dwordx4 v242, v[124:127], s[60:61]
	v_pk_mul_f32 v[120:121], v[120:121], v[228:229] op_sel:[0,1] op_sel_hi:[1,1]
	v_pk_mul_f32 v[122:123], v[122:123], v[228:229] op_sel:[0,1] op_sel_hi:[1,1]
	global_store_dwordx4 v242, v[120:123], s[60:61] offset:64
	v_pk_mul_f32 v[116:117], v[116:117], v[228:229] op_sel:[0,1] op_sel_hi:[1,1]
	v_pk_mul_f32 v[118:119], v[118:119], v[228:229] op_sel:[0,1] op_sel_hi:[1,1]
	global_store_dwordx4 v242, v[116:119], s[60:61] offset:512
	v_pk_mul_f32 v[112:113], v[112:113], v[228:229] op_sel:[0,1] op_sel_hi:[1,1]
	v_pk_mul_f32 v[114:115], v[114:115], v[228:229] op_sel:[0,1] op_sel_hi:[1,1]
	v_pk_mul_f32 v[112:113], v[112:113], v[224:225]
	v_pk_mul_f32 v[114:115], v[114:115], v[226:227]
	global_store_dwordx4 v242, v[112:115], s[60:61] offset:576
	v_add_u32_e32 v242, 32, v195
	v_lshl_add_u32 v242, v242, 13, v156
	v_pk_mul_f32 v[92:93], v[92:93], v[230:231] op_sel_hi:[1,0]
	v_pk_mul_f32 v[94:95], v[94:95], v[230:231] op_sel_hi:[1,0]
	global_store_dwordx4 v242, v[92:95], s[60:61]
	v_pk_mul_f32 v[88:89], v[88:89], v[230:231] op_sel_hi:[1,0]
	v_pk_mul_f32 v[90:91], v[90:91], v[230:231] op_sel_hi:[1,0]
	global_store_dwordx4 v242, v[88:91], s[60:61] offset:64
	v_pk_mul_f32 v[84:85], v[84:85], v[230:231] op_sel_hi:[1,0]
	v_pk_mul_f32 v[86:87], v[86:87], v[230:231] op_sel_hi:[1,0]
	global_store_dwordx4 v242, v[84:87], s[60:61] offset:512
	v_pk_mul_f32 v[80:81], v[80:81], v[230:231] op_sel_hi:[1,0]
	v_pk_mul_f32 v[82:83], v[82:83], v[230:231] op_sel_hi:[1,0]
	v_pk_mul_f32 v[80:81], v[80:81], v[224:225]
	v_pk_mul_f32 v[82:83], v[82:83], v[226:227]
	global_store_dwordx4 v242, v[80:83], s[60:61] offset:576
	v_add_u32_e32 v242, 48, v195
	v_lshl_add_u32 v242, v242, 13, v156
	v_pk_mul_f32 v[76:77], v[76:77], v[230:231] op_sel:[0,1] op_sel_hi:[1,1]
	v_pk_mul_f32 v[78:79], v[78:79], v[230:231] op_sel:[0,1] op_sel_hi:[1,1]
	global_store_dwordx4 v242, v[76:79], s[60:61]
	v_pk_mul_f32 v[72:73], v[72:73], v[230:231] op_sel:[0,1] op_sel_hi:[1,1]
	v_pk_mul_f32 v[74:75], v[74:75], v[230:231] op_sel:[0,1] op_sel_hi:[1,1]
	global_store_dwordx4 v242, v[72:75], s[60:61] offset:64
	v_pk_mul_f32 v[68:69], v[68:69], v[230:231] op_sel:[0,1] op_sel_hi:[1,1]
	v_pk_mul_f32 v[70:71], v[70:71], v[230:231] op_sel:[0,1] op_sel_hi:[1,1]
	global_store_dwordx4 v242, v[68:71], s[60:61] offset:512
	v_pk_mul_f32 v[64:65], v[64:65], v[230:231] op_sel:[0,1] op_sel_hi:[1,1]
	v_pk_mul_f32 v[66:67], v[66:67], v[230:231] op_sel:[0,1] op_sel_hi:[1,1]
	v_pk_mul_f32 v[64:65], v[64:65], v[224:225]
	v_pk_mul_f32 v[66:67], v[66:67], v[226:227]
	global_store_dwordx4 v242, v[64:67], s[60:61] offset:576
	v_add_u32_e32 v242, 128, v195
	v_lshl_add_u32 v242, v242, 13, v156
	v_pk_mul_f32 v[60:61], v[60:61], v[232:233] op_sel_hi:[1,0]
	v_pk_mul_f32 v[62:63], v[62:63], v[232:233] op_sel_hi:[1,0]
	global_store_dwordx4 v242, v[60:63], s[60:61]
	v_pk_mul_f32 v[56:57], v[56:57], v[232:233] op_sel_hi:[1,0]
	v_pk_mul_f32 v[58:59], v[58:59], v[232:233] op_sel_hi:[1,0]
	global_store_dwordx4 v242, v[56:59], s[60:61] offset:64
	v_pk_mul_f32 v[52:53], v[52:53], v[232:233] op_sel_hi:[1,0]
	v_pk_mul_f32 v[54:55], v[54:55], v[232:233] op_sel_hi:[1,0]
	global_store_dwordx4 v242, v[52:55], s[60:61] offset:512
	v_pk_mul_f32 v[48:49], v[48:49], v[232:233] op_sel_hi:[1,0]
	v_pk_mul_f32 v[50:51], v[50:51], v[232:233] op_sel_hi:[1,0]
	v_pk_mul_f32 v[48:49], v[48:49], v[224:225]
	v_pk_mul_f32 v[50:51], v[50:51], v[226:227]
	global_store_dwordx4 v242, v[48:51], s[60:61] offset:576
	v_add_u32_e32 v242, 144, v195
	v_lshl_add_u32 v242, v242, 13, v156
	v_pk_mul_f32 v[44:45], v[44:45], v[232:233] op_sel:[0,1] op_sel_hi:[1,1]
	v_pk_mul_f32 v[46:47], v[46:47], v[232:233] op_sel:[0,1] op_sel_hi:[1,1]
	global_store_dwordx4 v242, v[44:47], s[60:61]
	v_pk_mul_f32 v[40:41], v[40:41], v[232:233] op_sel:[0,1] op_sel_hi:[1,1]
	v_pk_mul_f32 v[42:43], v[42:43], v[232:233] op_sel:[0,1] op_sel_hi:[1,1]
	global_store_dwordx4 v242, v[40:43], s[60:61] offset:64
	v_pk_mul_f32 v[36:37], v[36:37], v[232:233] op_sel:[0,1] op_sel_hi:[1,1]
	v_pk_mul_f32 v[38:39], v[38:39], v[232:233] op_sel:[0,1] op_sel_hi:[1,1]
	global_store_dwordx4 v242, v[36:39], s[60:61] offset:512
	v_pk_mul_f32 v[32:33], v[32:33], v[232:233] op_sel:[0,1] op_sel_hi:[1,1]
	v_pk_mul_f32 v[34:35], v[34:35], v[232:233] op_sel:[0,1] op_sel_hi:[1,1]
	v_pk_mul_f32 v[32:33], v[32:33], v[224:225]
	v_pk_mul_f32 v[34:35], v[34:35], v[226:227]
	global_store_dwordx4 v242, v[32:35], s[60:61] offset:576
	v_add_u32_e32 v242, 160, v195
	v_lshl_add_u32 v242, v242, 13, v156
	v_pk_mul_f32 v[28:29], v[28:29], v[234:235] op_sel_hi:[1,0]
	v_pk_mul_f32 v[30:31], v[30:31], v[234:235] op_sel_hi:[1,0]
	global_store_dwordx4 v242, v[28:31], s[60:61]
	v_pk_mul_f32 v[24:25], v[24:25], v[234:235] op_sel_hi:[1,0]
	v_pk_mul_f32 v[26:27], v[26:27], v[234:235] op_sel_hi:[1,0]
	global_store_dwordx4 v242, v[24:27], s[60:61] offset:64
	v_pk_mul_f32 v[20:21], v[20:21], v[234:235] op_sel_hi:[1,0]
	v_pk_mul_f32 v[22:23], v[22:23], v[234:235] op_sel_hi:[1,0]
	global_store_dwordx4 v242, v[20:23], s[60:61] offset:512
	v_pk_mul_f32 v[16:17], v[16:17], v[234:235] op_sel_hi:[1,0]
	v_pk_mul_f32 v[18:19], v[18:19], v[234:235] op_sel_hi:[1,0]
	v_pk_mul_f32 v[16:17], v[16:17], v[224:225]
	v_pk_mul_f32 v[18:19], v[18:19], v[226:227]
	global_store_dwordx4 v242, v[16:19], s[60:61] offset:576
	v_add_u32_e32 v242, 176, v195
	v_lshl_add_u32 v242, v242, 13, v156
	v_pk_mul_f32 v[12:13], v[12:13], v[234:235] op_sel:[0,1] op_sel_hi:[1,1]
	v_pk_mul_f32 v[14:15], v[14:15], v[234:235] op_sel:[0,1] op_sel_hi:[1,1]
	global_store_dwordx4 v242, v[12:15], s[60:61]
	v_pk_mul_f32 v[8:9], v[8:9], v[234:235] op_sel:[0,1] op_sel_hi:[1,1]
	v_pk_mul_f32 v[10:11], v[10:11], v[234:235] op_sel:[0,1] op_sel_hi:[1,1]
	global_store_dwordx4 v242, v[8:11], s[60:61] offset:64
	v_pk_mul_f32 v[4:5], v[4:5], v[234:235] op_sel:[0,1] op_sel_hi:[1,1]
	v_pk_mul_f32 v[6:7], v[6:7], v[234:235] op_sel:[0,1] op_sel_hi:[1,1]
	global_store_dwordx4 v242, v[4:7], s[60:61] offset:512
	v_pk_mul_f32 v[0:1], v[0:1], v[234:235] op_sel:[0,1] op_sel_hi:[1,1]
	v_pk_mul_f32 v[2:3], v[2:3], v[234:235] op_sel:[0,1] op_sel_hi:[1,1]
	v_pk_mul_f32 v[0:1], v[0:1], v[224:225]
	v_pk_mul_f32 v[2:3], v[2:3], v[226:227]
	global_store_dwordx4 v242, v[0:3], s[60:61] offset:576
	s_mov_b64 s[2:3], -1
	s_cmp_eq_u32 s66, 3
	s_cbranch_scc1 .LBB0_527
	s_andn2_b64 vcc, exec, s[8:9]
	s_cbranch_vccnz .LBB0_526
	s_barrier
	s_branch .LBB0_526
